# residual epilogues (out-proj/down-proj): dummy dword loads touch all 16 residual-stream pieces up front so the serialized load-wait round trips hit L2
# baseline (speedup 1.0000x reference)
; DI unsigned pk2(float lo, float hi) { f32x2_t v = {lo, hi}; bf16x2_t b = __builtin_convertvector(v, bf16x2_t); return __builtin_bit_cast(unsigned, b); }
; DI float bflo(unsigned u) { return __uint_as_float(u << 16); }
; DI float bfhi(unsigned u) { return __uint_as_float(u & 0xffff0000u); }
;     DI void operator()(pg8::f32x4 (&acc)[2][2][4][2], const pg8::Unit& u, int wr, int wc, int fr, int fq) const {
;     ...
;         const int colb = u.pn * 256 + wc * 32 + 8 * fq;
; #pragma unroll
;         for (int ai = 0; ai < 2; ++ai)
; #pragma unroll
;             for (int m = 0; m < 4; ++m) {
;                 const int rl = ai * 128 + wr * 64 + m * 16 + fr; const float r1 = S[rl];
;                 const size_t ro = (size_t)(u.pm * 256 + rl) * 1024 + colb;
;                 float q = 0.f;
; #pragma unroll
;                 for (int bj = 0; bj < 2; ++bj) {
;                     const v4u xw = *(const v4u*)(XB + ro + bj * 128);
;                     const v4f g0 = *(const v4f*)(gpost + colb + bj * 128), g1 = *(const v4f*)(gpost + colb + bj * 128 + 4);
;                     const pg8::f32x4 a0 = acc[ai][bj][m][0], a1 = acc[ai][bj][m][1];
;                     float v[8];
;                     v[0] = bflo(xw.x) + a0[0] * r1 * g0[0]; v[1] = bfhi(xw.x) + a0[1] * r1 * g0[1]; v[2] = bflo(xw.y) + a0[2] * r1 * g0[2]; v[3] = bfhi(xw.y) + a0[3] * r1 * g0[3];
;                     v[4] = bflo(xw.z) + a1[0] * r1 * g1[0]; v[5] = bfhi(xw.z) + a1[1] * r1 * g1[1]; v[6] = bflo(xw.w) + a1[2] * r1 * g1[2]; v[7] = bfhi(xw.w) + a1[3] * r1 * g1[3];
;                     q += ((v[0] * v[0] + v[1] * v[1]) + (v[2] * v[2] + v[3] * v[3])) + ((v[4] * v[4] + v[5] * v[5]) + (v[6] * v[6] + v[7] * v[7]));
;                     if (last) { *(v4f*)(OUT + ro + bj * 128) = (v4f){v[0], v[1], v[2], v[3]}; *(v4f*)(OUT + ro + bj * 128 + 4) = (v4f){v[4], v[5], v[6], v[7]}; }
;                     else { v4u w; w.x = pk2(v[0], v[1]); w.y = pk2(v[2], v[3]); w.z = pk2(v[4], v[5]); w.w = pk2(v[6], v[7]); *(v4u*)(XB + ro + bj * 128) = w; }
.LBB0_132:
	s_or_b64 exec, exec, s[26:27]
	v_readlane_b32 s0, v255, 7
	v_readlane_b32 s1, v255, 8
	s_lshl_b64 s[22:23], s[0:1], 2
	s_add_u32 s26, s48, s22
	v_add_u32_e32 v134, v152, v158
	s_addc_u32 s27, s49, s23
	v_lshl_or_b32 v132, s8, 8, v160
	s_waitcnt lgkmcnt(0)
	v_ashrrev_i32_e32 v135, 31, v134
	s_add_u32 s22, s24, 0x7000000
	v_ashrrev_i32_e32 v133, 31, v132
	v_lshlrev_b64 v[136:137], 10, v[134:135]
	s_addc_u32 s23, s25, 0
	v_lshl_add_u64 v[150:151], v[136:137], 0, v[132:133]
	s_waitcnt lgkmcnt(0)
	s_barrier
	v_lshl_add_u64 v[136:137], v[150:151], 1, s[22:23]
	v_lshl_add_u64 v[130:131], v[132:133], 2, s[26:27]
	ds_read_b32 v148, v169
	global_load_dwordx4 v[154:157], v[136:137], off
	global_load_dwordx4 v[182:185], v[130:131], off offset:16
	global_load_dwordx4 v[186:189], v[130:131], off
	s_mov_b32 s99, 0
	global_load_dword v250, v[136:137], off offset:256
	s_mov_b32 s98, 0x8000
	v_lshl_add_u64 v[238:239], v[136:137], 0, s[98:99]
	global_load_dword v250, v[238:239], off
	global_load_dword v250, v[238:239], off offset:256
	s_mov_b32 s98, 0x10000
	v_lshl_add_u64 v[238:239], v[136:137], 0, s[98:99]
	global_load_dword v250, v[238:239], off
	global_load_dword v250, v[238:239], off offset:256
	s_mov_b32 s98, 0x18000
	v_lshl_add_u64 v[238:239], v[136:137], 0, s[98:99]
	global_load_dword v250, v[238:239], off
	global_load_dword v250, v[238:239], off offset:256
	s_mov_b32 s98, 0x40000
	v_lshl_add_u64 v[238:239], v[136:137], 0, s[98:99]
	global_load_dword v250, v[238:239], off
	global_load_dword v250, v[238:239], off offset:256
	s_mov_b32 s98, 0x48000
	v_lshl_add_u64 v[238:239], v[136:137], 0, s[98:99]
	global_load_dword v250, v[238:239], off
	global_load_dword v250, v[238:239], off offset:256
	s_mov_b32 s98, 0x50000
	v_lshl_add_u64 v[238:239], v[136:137], 0, s[98:99]
	global_load_dword v250, v[238:239], off
	global_load_dword v250, v[238:239], off offset:256
	s_mov_b32 s98, 0x58000
	v_lshl_add_u64 v[238:239], v[136:137], 0, s[98:99]
	global_load_dword v250, v[238:239], off
	global_load_dword v250, v[238:239], off offset:256
	s_mov_b64 s[26:27], -1
	s_and_b64 vcc, exec, s[18:19]
	s_waitcnt lgkmcnt(0)
	v_pk_mul_f32 v[128:129], v[128:129], v[148:149] op_sel_hi:[1,0]
	v_pk_mul_f32 v[122:123], v[122:123], v[148:149] op_sel_hi:[1,0]
	v_pk_mul_f32 v[126:127], v[126:127], v[148:149] op_sel_hi:[1,0]
	v_pk_mul_f32 v[124:125], v[124:125], v[148:149] op_sel_hi:[1,0]
	s_waitcnt vmcnt(0)
	v_lshlrev_b32_e32 v172, 16, v154
	v_and_b32_e32 v173, 0xffff0000, v154
	v_lshlrev_b32_e32 v154, 16, v155
	v_and_b32_e32 v155, 0xffff0000, v155
	v_pk_fma_f32 v[128:129], v[128:129], v[188:189], v[154:155]
	v_lshlrev_b32_e32 v154, 16, v156
	v_and_b32_e32 v155, 0xffff0000, v156
	v_pk_fma_f32 v[122:123], v[122:123], v[182:183], v[154:155]
	v_lshlrev_b32_e32 v154, 16, v157
	v_and_b32_e32 v155, 0xffff0000, v157
	v_pk_fma_f32 v[126:127], v[126:127], v[186:187], v[172:173]
	v_pk_fma_f32 v[124:125], v[124:125], v[184:185], v[154:155]
	s_cbranch_vccz .LBB0_134
	v_cvt_pk_bf16_f32 v154, v126, v127
	v_cvt_pk_bf16_f32 v155, v128, v129
	v_cvt_pk_bf16_f32 v156, v122, v123
	v_cvt_pk_bf16_f32 v157, v124, v125
	global_store_dwordx4 v[136:137], v[154:157], off
	s_mov_b64 s[26:27], 0

; DI unsigned pk2(float lo, float hi) { f32x2_t v = {lo, hi}; bf16x2_t b = __builtin_convertvector(v, bf16x2_t); return __builtin_bit_cast(unsigned, b); }
; DI float bflo(unsigned u) { return __uint_as_float(u << 16); }
; DI float bfhi(unsigned u) { return __uint_as_float(u & 0xffff0000u); }
;     DI void operator()(pg8::f32x4 (&acc)[2][2][4][2], const pg8::Unit& u, int wr, int wc, int fr, int fq) const {
;     ...
;         const int colb = u.pn * 256 + wc * 32 + 8 * fq;
; #pragma unroll
;         for (int ai = 0; ai < 2; ++ai)
; #pragma unroll
;             for (int m = 0; m < 4; ++m) {
;                 const int rl = ai * 128 + wr * 64 + m * 16 + fr; const float r1 = S[rl];
;                 const size_t ro = (size_t)(u.pm * 256 + rl) * 1024 + colb;
;                 float q = 0.f;
; #pragma unroll
;                 for (int bj = 0; bj < 2; ++bj) {
;                     const v4u xw = *(const v4u*)(XB + ro + bj * 128);
;                     const v4f g0 = *(const v4f*)(gpost + colb + bj * 128), g1 = *(const v4f*)(gpost + colb + bj * 128 + 4);
;                     const pg8::f32x4 a0 = acc[ai][bj][m][0], a1 = acc[ai][bj][m][1];
;                     float v[8];
;                     v[0] = bflo(xw.x) + a0[0] * r1 * g0[0]; v[1] = bfhi(xw.x) + a0[1] * r1 * g0[1]; v[2] = bflo(xw.y) + a0[2] * r1 * g0[2]; v[3] = bfhi(xw.y) + a0[3] * r1 * g0[3];
;                     v[4] = bflo(xw.z) + a1[0] * r1 * g1[0]; v[5] = bfhi(xw.z) + a1[1] * r1 * g1[1]; v[6] = bflo(xw.w) + a1[2] * r1 * g1[2]; v[7] = bfhi(xw.w) + a1[3] * r1 * g1[3];
;                     q += ((v[0] * v[0] + v[1] * v[1]) + (v[2] * v[2] + v[3] * v[3])) + ((v[4] * v[4] + v[5] * v[5]) + (v[6] * v[6] + v[7] * v[7]));
;                     if (last) { *(v4f*)(OUT + ro + bj * 128) = (v4f){v[0], v[1], v[2], v[3]}; *(v4f*)(OUT + ro + bj * 128 + 4) = (v4f){v[4], v[5], v[6], v[7]}; }
;                     else { v4u w; w.x = pk2(v[0], v[1]); w.y = pk2(v[2], v[3]); w.z = pk2(v[4], v[5]); w.w = pk2(v[6], v[7]); *(v4u*)(XB + ro + bj * 128) = w; }
;                 }
;                 q += __shfl_xor(q, 16); q += __shfl_xor(q, 32);
;                 if (fq == 0) slots2[(size_t)(u.pm * 256 + rl) * 16 + u.pn * 4 + wc] = q;
.LBB0_426:
	s_or_b64 exec, exec, s[24:25]
	v_readlane_b32 s0, v255, 7
	v_lshl_or_b32 v0, s20, 8, v162
	v_readlane_b32 s1, v255, 8
	v_ashrrev_i32_e32 v1, 31, v0
	v_add_u32_e32 v4, v150, v160
	s_lshl_b64 s[22:23], s[0:1], 2
	v_lshl_add_u64 v[2:3], v[0:1], 1, s[26:27]
	s_mov_b64 s[24:25], 0x7000000
	v_ashrrev_i32_e32 v5, 31, v4
	s_add_u32 s22, s28, s22
	v_lshl_add_u64 v[2:3], v[2:3], 0, s[24:25]
	v_lshlrev_b64 v[6:7], 11, v[4:5]
	s_addc_u32 s23, s29, s23
	s_waitcnt lgkmcnt(0)
	s_barrier
	v_lshl_add_u64 v[6:7], v[2:3], 0, v[6:7]
	v_lshl_add_u64 v[0:1], v[0:1], 2, s[22:23]
	ds_read_b32 v64, v174
	global_load_dwordx4 v[152:155], v[6:7], off
	global_load_dwordx4 v[156:159], v[0:1], off offset:16
	global_load_dwordx4 v[180:183], v[0:1], off
	s_mov_b32 s99, 0
	global_load_dword v250, v[6:7], off offset:256
	s_mov_b32 s98, 0x8000
	v_lshl_add_u64 v[238:239], v[6:7], 0, s[98:99]
	global_load_dword v250, v[238:239], off
	global_load_dword v250, v[238:239], off offset:256
	s_mov_b32 s98, 0x10000
	v_lshl_add_u64 v[238:239], v[6:7], 0, s[98:99]
	global_load_dword v250, v[238:239], off
	global_load_dword v250, v[238:239], off offset:256
	s_mov_b32 s98, 0x18000
	v_lshl_add_u64 v[238:239], v[6:7], 0, s[98:99]
	global_load_dword v250, v[238:239], off
	global_load_dword v250, v[238:239], off offset:256
	s_mov_b32 s98, 0x40000
	v_lshl_add_u64 v[238:239], v[6:7], 0, s[98:99]
	global_load_dword v250, v[238:239], off
	global_load_dword v250, v[238:239], off offset:256
	s_mov_b32 s98, 0x48000
	v_lshl_add_u64 v[238:239], v[6:7], 0, s[98:99]
	global_load_dword v250, v[238:239], off
	global_load_dword v250, v[238:239], off offset:256
	s_mov_b32 s98, 0x50000
	v_lshl_add_u64 v[238:239], v[6:7], 0, s[98:99]
	global_load_dword v250, v[238:239], off
	global_load_dword v250, v[238:239], off offset:256
	s_mov_b32 s98, 0x58000
	v_lshl_add_u64 v[238:239], v[6:7], 0, s[98:99]
	global_load_dword v250, v[238:239], off
	global_load_dword v250, v[238:239], off offset:256
	s_lshl_b32 s20, s20, 2
	s_ashr_i32 s21, s20, 31
	s_lshl_b64 s[20:21], s[20:21], 2
	s_waitcnt lgkmcnt(0)
	v_pk_mul_f32 v[148:149], v[148:149], v[64:65] op_sel_hi:[1,0]
	v_pk_mul_f32 v[144:145], v[144:145], v[64:65] op_sel_hi:[1,0]
	v_pk_mul_f32 v[146:147], v[146:147], v[64:65] op_sel_hi:[1,0]
	v_pk_mul_f32 v[130:131], v[130:131], v[64:65] op_sel_hi:[1,0]
	v_pk_mul_f32 v[126:127], v[126:127], v[64:65] op_sel_hi:[1,0]
	v_pk_mul_f32 v[124:125], v[124:125], v[64:65] op_sel_hi:[1,0]
	v_pk_mul_f32 v[122:123], v[122:123], v[64:65] op_sel_hi:[1,0]
	v_pk_mul_f32 v[128:129], v[128:129], v[64:65] op_sel_hi:[1,0]
	s_add_u32 s8, s26, s20
	s_addc_u32 s10, s27, s21
	s_add_u32 s8, s8, s50
	s_addc_u32 s10, s10, 0
	s_add_u32 s20, s8, 0x1c900000
	s_addc_u32 s21, s10, 0
	s_waitcnt vmcnt(0)
	v_lshlrev_b32_e32 v172, 16, v152
	v_and_b32_e32 v173, 0xffff0000, v152
	v_pk_fma_f32 v[172:173], v[148:149], v[180:181], v[172:173]
	v_lshlrev_b32_e32 v148, 16, v153
	v_and_b32_e32 v149, 0xffff0000, v153
	v_pk_fma_f32 v[180:181], v[144:145], v[182:183], v[148:149]
	v_lshlrev_b32_e32 v144, 16, v154
	v_and_b32_e32 v145, 0xffff0000, v154
	v_pk_fma_f32 v[156:157], v[146:147], v[156:157], v[144:145]
	v_lshlrev_b32_e32 v144, 16, v155
	v_and_b32_e32 v145, 0xffff0000, v155
	v_pk_fma_f32 v[158:159], v[130:131], v[158:159], v[144:145]
	v_cvt_pk_bf16_f32 v152, v172, v173
	v_cvt_pk_bf16_f32 v153, v180, v181
	v_cvt_pk_bf16_f32 v154, v156, v157
	v_cvt_pk_bf16_f32 v155, v158, v159
	global_store_dwordx4 v[6:7], v[152:155], off
	v_pk_mul_f32 v[144:145], v[180:181], v[180:181]
	v_pk_mul_f32 v[146:147], v[156:157], v[156:157]
	v_pk_mul_f32 v[148:149], v[158:159], v[158:159]
	global_load_dwordx4 v[152:155], v[6:7], off offset:256
	global_load_dwordx4 v[156:159], v[0:1], off offset:528
	global_load_dwordx4 v[180:183], v[0:1], off offset:512
	v_pk_mul_f32 v[130:131], v[172:173], v[172:173]
	v_add_f32_e32 v64, v148, v149
	v_add_f32_e32 v146, v146, v147
	v_add_f32_e32 v144, v144, v145
	v_add_f32_e32 v130, v130, v131
	v_add_f32_e32 v64, v146, v64
	v_add_f32_e32 v130, v130, v144
	v_add_f32_e32 v64, v130, v64
	s_waitcnt vmcnt(2)
	v_lshlrev_b32_e32 v172, 16, v152
	v_and_b32_e32 v173, 0xffff0000, v152
	v_lshlrev_b32_e32 v152, 16, v153
	v_and_b32_e32 v153, 0xffff0000, v153
	s_waitcnt vmcnt(0)
	v_pk_fma_f32 v[126:127], v[126:127], v[182:183], v[152:153]
	v_lshlrev_b32_e32 v152, 16, v154
	v_and_b32_e32 v153, 0xffff0000, v154
	v_pk_fma_f32 v[124:125], v[124:125], v[156:157], v[152:153]
	v_lshlrev_b32_e32 v152, 16, v155
	v_and_b32_e32 v153, 0xffff0000, v155
	v_pk_fma_f32 v[152:153], v[122:123], v[158:159], v[152:153]
	v_pk_fma_f32 v[128:129], v[128:129], v[180:181], v[172:173]
	v_pk_mul_f32 v[156:157], v[124:125], v[124:125]
	v_pk_mul_f32 v[158:159], v[152:153], v[152:153]
	v_pk_mul_f32 v[122:123], v[128:129], v[128:129]
	v_pk_mul_f32 v[154:155], v[126:127], v[126:127]
	v_add_f32_e32 v130, v158, v159
	v_add_f32_e32 v131, v156, v157
	v_add_f32_e32 v130, v131, v130
	v_add_f32_e32 v131, v154, v155
	v_add_f32_e32 v122, v122, v123
	v_add_f32_e32 v122, v122, v131
	v_add_f32_e32 v122, v122, v130
	v_add_f32_e32 v64, v64, v122
	v_cvt_pk_bf16_f32 v122, v128, v129
	v_cvt_pk_bf16_f32 v123, v126, v127
	v_cvt_pk_bf16_f32 v124, v124, v125
	v_cvt_pk_bf16_f32 v125, v152, v153
	global_store_dwordx4 v[6:7], v[122:125], off offset:256
	ds_bpermute_b32 v6, v177, v64
	s_waitcnt lgkmcnt(0)
	v_add_f32_e32 v6, v64, v6
	ds_bpermute_b32 v7, v178, v6
	s_and_saveexec_b64 s[22:23], s[38:39]
	s_cbranch_execz .LBB0_428
	v_lshlrev_b64 v[4:5], 6, v[4:5]
	v_lshl_add_u64 v[4:5], s[20:21], 0, v[4:5]
	s_waitcnt lgkmcnt(0)
	v_add_f32_e32 v6, v6, v7
	global_store_dword v[4:5], v6, off
